# attention early waves: l-sum hoisted before P.V, then fused P.V + QK(t+1) with K fragment reads interleaved between the P.V MFMAs
# baseline (speedup 1.0000x reference)
; #define AT_LAS __attribute__((address_space(3)))
; #define AT_PK(P, B) cvtpk_s(P[B], P[B + 1])
; __device__ __forceinline__ void pv(f32x16 (&o)[2], AT_LAS const char* vp, const u32x4& pw0, const u32x4& pw1, const u32x4& pw2, const u32x4& pw3) {
; #pragma unroll
;     for (int d0 = 0; d0 < 2; ++d0) { s16x4 lo[4], hh[4];
; #pragma unroll
;         for (int ks = 0; ks < 4; ++ks) { lo[ks] = vtr(vp + d0 * 4096 + ks * 1024); hh[ks] = vtr(vp + d0 * 4096 + ks * 1024 + 512); }
;     ...
;         o[d0] = __builtin_amdgcn_mfma_f32_32x32x16_bf16(__builtin_bit_cast(bf16x8, pw0), AT_VF(0), o[d0], 0, 0, 0);
;         o[d0] = __builtin_amdgcn_mfma_f32_32x32x16_bf16(__builtin_bit_cast(bf16x8, pw1), AT_VF(1), o[d0], 0, 0, 0);
;         o[d0] = __builtin_amdgcn_mfma_f32_32x32x16_bf16(__builtin_bit_cast(bf16x8, pw2), AT_VF(2), o[d0], 0, 0, 0);
;         o[d0] = __builtin_amdgcn_mfma_f32_32x32x16_bf16(__builtin_bit_cast(bf16x8, pw3), AT_VF(3), o[d0], 0, 0, 0);
;     ...
;     }
; }
; __device__ __forceinline__ void qkt(f32x16& p0, f32x16& p1, AT_LAS const char* kb, const bf16x8 (&qr)[6], const f32x16& negm) {
;     bf16x8 kf[12];
; #pragma unroll
;     for (int d0 = 0; d0 < 6; ++d0) { kf[2 * d0] = *(AT_LAS const bf16x8*)(kb + d0 * 2048); kf[2 * d0 + 1] = *(AT_LAS const bf16x8*)(kb + d0 * 2048 + 512); }
;     __builtin_amdgcn_sched_barrier(0);
; template <int THRL>
; __device__ __forceinline__ void attn_item(int b, int h, int s, const bf16_t* Q, const bf16_t* KN, const bf16_t* KR, const bf16_t* V, const float* goa  , bf16_t* Y, float* ssqy, AT_LAS char* shm, int wid0) {
;     ...
;                 float sacc = 0.f;
; #pragma unroll
;                 for (int r = 0; r < 16; ++r) { p0[r] = __builtin_amdgcn_exp2f(p0[r]); p1[r] = __builtin_amdgcn_exp2f(p1[r]); sacc += p0[r] + p1[r]; }
;                 l_reg += sacc;
;     ...
;                 pw0 = (u32x4){AT_PK(p0, 0), AT_PK(p0, 2), AT_PK(p0, 4), AT_PK(p0, 6)}; pw1 = (u32x4){AT_PK(p0, 8), AT_PK(p0, 10), AT_PK(p0, 12), AT_PK(p0, 14)};
;                 pw2 = (u32x4){AT_PK(p1, 0), AT_PK(p1, 2), AT_PK(p1, 4), AT_PK(p1, 6)}; pw3 = (u32x4){AT_PK(p1, 8), AT_PK(p1, 10), AT_PK(p1, 12), AT_PK(p1, 14)};
;     ...
;                 if (late) have = true;
;                 else pv(o, vp0 + (t & 3) * VSLOTB, pw0, pw1, pw2, pw3);
;             }
;             if (!late) { if (t + 1 < NT && (jb + 1) <= wq) qkt(p0, p1, kp0 + ((t + 1) & 3) * KSLOTB, qr, negm); }
.LBB13_779:
	v_exp_f32_e32 v18, v18
	v_exp_f32_e32 v34, v34
	v_exp_f32_e32 v0, v19
	v_exp_f32_e32 v154, v35
	v_exp_f32_e32 v20, v20
	v_exp_f32_e32 v36, v36
	v_exp_f32_e32 v168, v21
	v_exp_f32_e32 v156, v37
	v_exp_f32_e32 v22, v22
	v_exp_f32_e32 v38, v38
	v_exp_f32_e32 v170, v23
	v_exp_f32_e32 v158, v39
	v_exp_f32_e32 v24, v24
	v_exp_f32_e32 v40, v40
	v_exp_f32_e32 v172, v25
	v_exp_f32_e32 v160, v41
	v_exp_f32_e32 v26, v26
	v_exp_f32_e32 v42, v42
	v_exp_f32_e32 v174, v27
	v_exp_f32_e32 v162, v43
	v_exp_f32_e32 v28, v28
	v_exp_f32_e32 v44, v44
	v_exp_f32_e32 v176, v29
	v_exp_f32_e32 v164, v45
	v_exp_f32_e32 v30, v30
	v_exp_f32_e32 v46, v46
	v_exp_f32_e32 v178, v31
	v_exp_f32_e32 v166, v47
	v_exp_f32_e32 v32, v32
	v_exp_f32_e32 v48, v48
	v_exp_f32_e32 v33, v33
	v_exp_f32_e32 v49, v49
	v_cvt_pk_bf16_f32 v110, v18, v0
	v_cvt_pk_bf16_f32 v111, v20, v168
	v_cvt_pk_bf16_f32 v112, v22, v170
	v_cvt_pk_bf16_f32 v113, v24, v172
	v_cvt_pk_bf16_f32 v106, v26, v174
	v_cvt_pk_bf16_f32 v107, v28, v176
	v_cvt_pk_bf16_f32 v108, v30, v178
	v_cvt_pk_bf16_f32 v109, v32, v33
	v_cvt_pk_bf16_f32 v118, v34, v154
	v_cvt_pk_bf16_f32 v119, v36, v156
	v_cvt_pk_bf16_f32 v120, v38, v158
	v_cvt_pk_bf16_f32 v121, v40, v160
	v_cvt_pk_bf16_f32 v114, v42, v162
	v_cvt_pk_bf16_f32 v115, v44, v164
	v_cvt_pk_bf16_f32 v116, v46, v166
	s_and_b64 vcc, exec, s[76:77]
	v_cvt_pk_bf16_f32 v117, v48, v49
	s_cbranch_vccnz .LBB13_781
	v_add_f32_e32 v18, v18, v34
	v_add_f32_e32 v0, v0, v154
	v_add_f32_e32 v20, v20, v36
	v_add_f32_e32 v168, v168, v156
	v_add_f32_e32 v22, v22, v38
	v_add_f32_e32 v170, v170, v158
	v_add_f32_e32 v24, v24, v40
	v_add_f32_e32 v172, v172, v160
	v_add_f32_e32 v26, v26, v42
	v_add_f32_e32 v174, v174, v162
	v_add_f32_e32 v28, v28, v44
	v_add_f32_e32 v176, v176, v164
	v_add_f32_e32 v30, v30, v46
	v_add_f32_e32 v178, v178, v166
	v_add_f32_e32 v32, v32, v48
	v_add_f32_e32 v33, v33, v49
	v_add_f32_e32 v18, v18, v0
	v_add_f32_e32 v20, v20, v168
	v_add_f32_e32 v22, v22, v170
	v_add_f32_e32 v24, v24, v172
	v_add_f32_e32 v26, v26, v174
	v_add_f32_e32 v28, v28, v176
	v_add_f32_e32 v30, v30, v178
	v_add_f32_e32 v32, v32, v33
	v_add_f32_e32 v18, v18, v20
	v_add_f32_e32 v22, v22, v24
	v_add_f32_e32 v26, v26, v28
	v_add_f32_e32 v30, v30, v32
	v_add_f32_e32 v18, v18, v22
	v_add_f32_e32 v26, v26, v30
	v_add_f32_e32 v0, v18, v26
	v_add_f32_e32 v153, v153, v0
	s_add_i32 s92, s9, -2
	s_cmp_lt_u32 s92, s79
	s_cselect_b64 vcc, -1, 0
	s_cmp_lt_i32 s84, s2
	s_cselect_b64 s[88:89], -1, 0
	s_and_b64 s[88:89], vcc, s[88:89]
	s_andn2_b64 vcc, exec, s[88:89]
	s_cbranch_vccnz .Lat0_e_pvonly
	s_and_b32 s84, s92, 3
	s_mulk_i32 s84, 0x3000
	v_add_u32_e32 v215, s84, v190
	s_waitcnt lgkmcnt(0)
	ds_read_b64_tr_b16 v[248:249], v214 offset:56320
	ds_read_b64_tr_b16 v[250:251], v214 offset:56832
	ds_read_b128 v[198:201], v215 offset:8192
	ds_read_b128 v[202:205], v215 offset:8704
	ds_read_b128 v[206:209], v215 offset:10240
	ds_read_b128 v[210:213], v215 offset:10752
	s_waitcnt lgkmcnt(6)
	v_mfma_f32_32x32x16_bf16 v[50:65], v[110:113], v[216:219], v[50:65]
	v_add_u32_e32 v236, s84, v252
	ds_read_b128 v[34:37], v236
	v_mfma_f32_32x32x16_bf16 v[50:65], v[106:109], v[220:223], v[50:65]
	ds_read_b128 v[154:157], v236 offset:4096
	v_mfma_f32_32x32x16_bf16 v[50:65], v[118:121], v[224:227], v[50:65]
	v_add_u32_e32 v239, s84, v253
	ds_read_b128 v[158:161], v239
	v_mfma_f32_32x32x16_bf16 v[50:65], v[114:117], v[228:231], v[50:65]
	ds_read_b128 v[162:165], v239 offset:4096
	v_mfma_f32_32x32x16_bf16 v[2:17], v[110:113], v[232:235], v[2:17]
	v_add_u32_e32 v236, s84, v254
	ds_read_b128 v[166:169], v236
	v_mfma_f32_32x32x16_bf16 v[2:17], v[106:109], v[240:243], v[2:17]
	ds_read_b128 v[170:173], v236 offset:4096
	v_mfma_f32_32x32x16_bf16 v[2:17], v[118:121], v[244:247], v[2:17]
	v_add_u32_e32 v239, s84, v255
	ds_read_b128 v[174:177], v239
	s_waitcnt lgkmcnt(11)
	v_mfma_f32_32x32x16_bf16 v[2:17], v[114:117], v[248:251], v[2:17]
	ds_read_b128 v[178:181], v239 offset:4096
	s_waitcnt lgkmcnt(7)
	v_mfma_f32_32x32x16_bf16 v[18:33], v[34:37], v[82:85], v[66:81]
	s_waitcnt lgkmcnt(6)
	v_mfma_f32_32x32x16_bf16 v[34:49], v[154:157], v[82:85], v[66:81]
	s_waitcnt lgkmcnt(5)
	v_mfma_f32_32x32x16_bf16 v[18:33], v[158:161], v[86:89], v[18:33]
	s_waitcnt lgkmcnt(4)
	v_mfma_f32_32x32x16_bf16 v[34:49], v[162:165], v[86:89], v[34:49]
	s_waitcnt lgkmcnt(3)
	v_mfma_f32_32x32x16_bf16 v[18:33], v[166:169], v[90:93], v[18:33]
	s_waitcnt lgkmcnt(2)
	v_mfma_f32_32x32x16_bf16 v[34:49], v[170:173], v[90:93], v[34:49]
	s_waitcnt lgkmcnt(1)
	v_mfma_f32_32x32x16_bf16 v[18:33], v[174:177], v[94:97], v[18:33]
	s_waitcnt lgkmcnt(0)
	v_mfma_f32_32x32x16_bf16 v[34:49], v[178:181], v[94:97], v[34:49]
	v_mfma_f32_32x32x16_bf16 v[18:33], v[198:201], v[98:101], v[18:33]
	v_mfma_f32_32x32x16_bf16 v[34:49], v[202:205], v[98:101], v[34:49]
	v_mfma_f32_32x32x16_bf16 v[18:33], v[206:209], v[102:105], v[18:33]
	v_mfma_f32_32x32x16_bf16 v[34:49], v[210:213], v[102:105], v[34:49]
	s_branch .LBB13_764
.Lat0_e_pvonly:
	s_waitcnt lgkmcnt(0)
	ds_read_b64_tr_b16 v[248:249], v214 offset:56320
	ds_read_b64_tr_b16 v[250:251], v214 offset:56832
	s_waitcnt lgkmcnt(2)
	v_mfma_f32_32x32x16_bf16 v[50:65], v[110:113], v[216:219], v[50:65]
	v_mfma_f32_32x32x16_bf16 v[50:65], v[106:109], v[220:223], v[50:65]
	v_mfma_f32_32x32x16_bf16 v[50:65], v[118:121], v[224:227], v[50:65]
	v_mfma_f32_32x32x16_bf16 v[50:65], v[114:117], v[228:231], v[50:65]
	v_mfma_f32_32x32x16_bf16 v[2:17], v[110:113], v[232:235], v[2:17]
	v_mfma_f32_32x32x16_bf16 v[2:17], v[106:109], v[240:243], v[2:17]
	v_mfma_f32_32x32x16_bf16 v[2:17], v[118:121], v[244:247], v[2:17]
	s_waitcnt lgkmcnt(0)
	v_mfma_f32_32x32x16_bf16 v[2:17], v[114:117], v[248:251], v[2:17]
	s_branch .LBB13_764

; #define AT_LAS __attribute__((address_space(3)))
; #define AT_PK(P, B) cvtpk_s(P[B], P[B + 1])
; __device__ __forceinline__ void pv(f32x16 (&o)[2], AT_LAS const char* vp, const u32x4& pw0, const u32x4& pw1, const u32x4& pw2, const u32x4& pw3) {
; #pragma unroll
;     for (int d0 = 0; d0 < 2; ++d0) { s16x4 lo[4], hh[4];
; #pragma unroll
;         for (int ks = 0; ks < 4; ++ks) { lo[ks] = vtr(vp + d0 * 4096 + ks * 1024); hh[ks] = vtr(vp + d0 * 4096 + ks * 1024 + 512); }
;     ...
;         o[d0] = __builtin_amdgcn_mfma_f32_32x32x16_bf16(__builtin_bit_cast(bf16x8, pw0), AT_VF(0), o[d0], 0, 0, 0);
;         o[d0] = __builtin_amdgcn_mfma_f32_32x32x16_bf16(__builtin_bit_cast(bf16x8, pw1), AT_VF(1), o[d0], 0, 0, 0);
;         o[d0] = __builtin_amdgcn_mfma_f32_32x32x16_bf16(__builtin_bit_cast(bf16x8, pw2), AT_VF(2), o[d0], 0, 0, 0);
;         o[d0] = __builtin_amdgcn_mfma_f32_32x32x16_bf16(__builtin_bit_cast(bf16x8, pw3), AT_VF(3), o[d0], 0, 0, 0);
;     ...
;     }
; }
; __device__ __forceinline__ void qkt(f32x16& p0, f32x16& p1, AT_LAS const char* kb, const bf16x8 (&qr)[6], const f32x16& negm) {
;     bf16x8 kf[12];
; #pragma unroll
;     for (int d0 = 0; d0 < 6; ++d0) { kf[2 * d0] = *(AT_LAS const bf16x8*)(kb + d0 * 2048); kf[2 * d0 + 1] = *(AT_LAS const bf16x8*)(kb + d0 * 2048 + 512); }
;     __builtin_amdgcn_sched_barrier(0);
; template <int THRL>
; __device__ __forceinline__ void attn_item(int b, int h, int s, const bf16_t* Q, const bf16_t* KN, const bf16_t* KR, const bf16_t* V, const float* goa  , bf16_t* Y, float* ssqy, AT_LAS char* shm, int wid0) {
;     ...
;                 float sacc = 0.f;
; #pragma unroll
;                 for (int r = 0; r < 16; ++r) { p0[r] = __builtin_amdgcn_exp2f(p0[r]); p1[r] = __builtin_amdgcn_exp2f(p1[r]); sacc += p0[r] + p1[r]; }
;                 l_reg += sacc;
;     ...
;                 pw0 = (u32x4){AT_PK(p0, 0), AT_PK(p0, 2), AT_PK(p0, 4), AT_PK(p0, 6)}; pw1 = (u32x4){AT_PK(p0, 8), AT_PK(p0, 10), AT_PK(p0, 12), AT_PK(p0, 14)};
;                 pw2 = (u32x4){AT_PK(p1, 0), AT_PK(p1, 2), AT_PK(p1, 4), AT_PK(p1, 6)}; pw3 = (u32x4){AT_PK(p1, 8), AT_PK(p1, 10), AT_PK(p1, 12), AT_PK(p1, 14)};
;     ...
;                 if (late) have = true;
;                 else pv(o, vp0 + (t & 3) * VSLOTB, pw0, pw1, pw2, pw3);
;             }
;             if (!late) { if (t + 1 < NT && (jb + 1) <= wq) qkt(p0, p1, kp0 + ((t + 1) & 3) * KSLOTB, qr, negm); }
.LBB13_1757:
	v_exp_f32_e32 v18, v18
	v_exp_f32_e32 v34, v34
	v_exp_f32_e32 v0, v19
	v_exp_f32_e32 v154, v35
	v_exp_f32_e32 v20, v20
	v_exp_f32_e32 v36, v36
	v_exp_f32_e32 v168, v21
	v_exp_f32_e32 v156, v37
	v_exp_f32_e32 v22, v22
	v_exp_f32_e32 v38, v38
	v_exp_f32_e32 v170, v23
	v_exp_f32_e32 v158, v39
	v_exp_f32_e32 v24, v24
	v_exp_f32_e32 v40, v40
	v_exp_f32_e32 v172, v25
	v_exp_f32_e32 v160, v41
	v_exp_f32_e32 v26, v26
	v_exp_f32_e32 v42, v42
	v_exp_f32_e32 v174, v27
	v_exp_f32_e32 v162, v43
	v_exp_f32_e32 v28, v28
	v_exp_f32_e32 v44, v44
	v_exp_f32_e32 v176, v29
	v_exp_f32_e32 v164, v45
	v_exp_f32_e32 v30, v30
	v_exp_f32_e32 v46, v46
	v_exp_f32_e32 v178, v31
	v_exp_f32_e32 v166, v47
	v_exp_f32_e32 v32, v32
	v_exp_f32_e32 v48, v48
	v_exp_f32_e32 v33, v33
	v_exp_f32_e32 v49, v49
	v_cvt_pk_bf16_f32 v110, v18, v0
	v_cvt_pk_bf16_f32 v111, v20, v168
	v_cvt_pk_bf16_f32 v112, v22, v170
	v_cvt_pk_bf16_f32 v113, v24, v172
	v_cvt_pk_bf16_f32 v106, v26, v174
	v_cvt_pk_bf16_f32 v107, v28, v176
	v_cvt_pk_bf16_f32 v108, v30, v178
	v_cvt_pk_bf16_f32 v109, v32, v33
	v_cvt_pk_bf16_f32 v118, v34, v154
	v_cvt_pk_bf16_f32 v119, v36, v156
	v_cvt_pk_bf16_f32 v120, v38, v158
	v_cvt_pk_bf16_f32 v121, v40, v160
	v_cvt_pk_bf16_f32 v114, v42, v162
	v_cvt_pk_bf16_f32 v115, v44, v164
	v_cvt_pk_bf16_f32 v116, v46, v166
	s_and_b64 vcc, exec, s[76:77]
	v_cvt_pk_bf16_f32 v117, v48, v49
	s_cbranch_vccnz .LBB13_1759
	v_add_f32_e32 v18, v18, v34
	v_add_f32_e32 v0, v0, v154
	v_add_f32_e32 v20, v20, v36
	v_add_f32_e32 v168, v168, v156
	v_add_f32_e32 v22, v22, v38
	v_add_f32_e32 v170, v170, v158
	v_add_f32_e32 v24, v24, v40
	v_add_f32_e32 v172, v172, v160
	v_add_f32_e32 v26, v26, v42
	v_add_f32_e32 v174, v174, v162
	v_add_f32_e32 v28, v28, v44
	v_add_f32_e32 v176, v176, v164
	v_add_f32_e32 v30, v30, v46
	v_add_f32_e32 v178, v178, v166
	v_add_f32_e32 v32, v32, v48
	v_add_f32_e32 v33, v33, v49
	v_add_f32_e32 v18, v18, v0
	v_add_f32_e32 v20, v20, v168
	v_add_f32_e32 v22, v22, v170
	v_add_f32_e32 v24, v24, v172
	v_add_f32_e32 v26, v26, v174
	v_add_f32_e32 v28, v28, v176
	v_add_f32_e32 v30, v30, v178
	v_add_f32_e32 v32, v32, v33
	v_add_f32_e32 v18, v18, v20
	v_add_f32_e32 v22, v22, v24
	v_add_f32_e32 v26, v26, v28
	v_add_f32_e32 v30, v30, v32
	v_add_f32_e32 v18, v18, v22
	v_add_f32_e32 v26, v26, v30
	v_add_f32_e32 v0, v18, v26
	v_add_f32_e32 v153, v153, v0
	s_add_i32 s92, s80, -2
	s_cmp_lt_u32 s92, s3
	s_cselect_b64 vcc, -1, 0
	s_cmp_lt_i32 s84, s33
	s_cselect_b64 s[88:89], -1, 0
	s_and_b64 s[88:89], vcc, s[88:89]
	s_andn2_b64 vcc, exec, s[88:89]
	s_cbranch_vccnz .Lat1_e_pvonly
	s_and_b32 s84, s92, 3
	s_mulk_i32 s84, 0x3000
	v_add_u32_e32 v215, s84, v190
	s_waitcnt lgkmcnt(0)
	ds_read_b64_tr_b16 v[248:249], v214 offset:56320
	ds_read_b64_tr_b16 v[250:251], v214 offset:56832
	ds_read_b128 v[198:201], v215 offset:8192
	ds_read_b128 v[202:205], v215 offset:8704
	ds_read_b128 v[206:209], v215 offset:10240
	ds_read_b128 v[210:213], v215 offset:10752
	s_waitcnt lgkmcnt(6)
	v_mfma_f32_32x32x16_bf16 v[50:65], v[110:113], v[216:219], v[50:65]
	v_add_u32_e32 v236, s84, v252
	ds_read_b128 v[34:37], v236
	v_mfma_f32_32x32x16_bf16 v[50:65], v[106:109], v[220:223], v[50:65]
	ds_read_b128 v[154:157], v236 offset:4096
	v_mfma_f32_32x32x16_bf16 v[50:65], v[118:121], v[224:227], v[50:65]
	v_add_u32_e32 v239, s84, v253
	ds_read_b128 v[158:161], v239
	v_mfma_f32_32x32x16_bf16 v[50:65], v[114:117], v[228:231], v[50:65]
	ds_read_b128 v[162:165], v239 offset:4096
	v_mfma_f32_32x32x16_bf16 v[2:17], v[110:113], v[232:235], v[2:17]
	v_add_u32_e32 v236, s84, v254
	ds_read_b128 v[166:169], v236
	v_mfma_f32_32x32x16_bf16 v[2:17], v[106:109], v[240:243], v[2:17]
	ds_read_b128 v[170:173], v236 offset:4096
	v_mfma_f32_32x32x16_bf16 v[2:17], v[118:121], v[244:247], v[2:17]
	v_add_u32_e32 v239, s84, v255
	ds_read_b128 v[174:177], v239
	s_waitcnt lgkmcnt(11)
	v_mfma_f32_32x32x16_bf16 v[2:17], v[114:117], v[248:251], v[2:17]
	ds_read_b128 v[178:181], v239 offset:4096
	s_waitcnt lgkmcnt(7)
	v_mfma_f32_32x32x16_bf16 v[18:33], v[34:37], v[82:85], v[66:81]
	s_waitcnt lgkmcnt(6)
	v_mfma_f32_32x32x16_bf16 v[34:49], v[154:157], v[82:85], v[66:81]
	s_waitcnt lgkmcnt(5)
	v_mfma_f32_32x32x16_bf16 v[18:33], v[158:161], v[86:89], v[18:33]
	s_waitcnt lgkmcnt(4)
	v_mfma_f32_32x32x16_bf16 v[34:49], v[162:165], v[86:89], v[34:49]
	s_waitcnt lgkmcnt(3)
	v_mfma_f32_32x32x16_bf16 v[18:33], v[166:169], v[90:93], v[18:33]
	s_waitcnt lgkmcnt(2)
	v_mfma_f32_32x32x16_bf16 v[34:49], v[170:173], v[90:93], v[34:49]
	s_waitcnt lgkmcnt(1)
	v_mfma_f32_32x32x16_bf16 v[18:33], v[174:177], v[94:97], v[18:33]
	s_waitcnt lgkmcnt(0)
	v_mfma_f32_32x32x16_bf16 v[34:49], v[178:181], v[94:97], v[34:49]
	v_mfma_f32_32x32x16_bf16 v[18:33], v[198:201], v[98:101], v[18:33]
	v_mfma_f32_32x32x16_bf16 v[34:49], v[202:205], v[98:101], v[34:49]
	v_mfma_f32_32x32x16_bf16 v[18:33], v[206:209], v[102:105], v[18:33]
	v_mfma_f32_32x32x16_bf16 v[34:49], v[210:213], v[102:105], v[34:49]
	s_branch .LBB13_1742
